# v34
# baseline (speedup 1.0000x reference)
.LBB0_275:
	s_lshl_b32 s65, s52, 6
	s_cmp_lt_u32 s52, 31
	s_cselect_b64 s[12:13], -1, 0
	s_cmp_gt_u32 s52, 30
	s_cbranch_scc1 .LBB0_277
	v_add_u32_e32 v68, s65, v133
	v_ashrrev_i32_e32 v69, 31, v68
	v_lshlrev_b64 v[68:69], 11, v[68:69]
	v_lshl_add_u64 v[76:77], v[88:89], 0, v[68:69]
	v_add_co_u32_e32 v80, vcc, 0x1000, v76
	s_nop 0
	v_addc_co_u32_e32 v81, vcc, 0, v77, vcc
.LBB0_277:
	s_cmp_eq_u32 s52, 0
	s_cbranch_scc1 .Lrnn_conv_c0
	v_lshlrev_b32_e32 v94, 16, v52
	v_and_b32_e32 v95, 0xffff0000, v52
	v_lshlrev_b32_e32 v96, 16, v53
	v_and_b32_e32 v97, 0xffff0000, v53
	v_lshlrev_b32_e32 v98, 16, v54
	v_and_b32_e32 v99, 0xffff0000, v54
	v_lshlrev_b32_e32 v100, 16, v55
	v_and_b32_e32 v101, 0xffff0000, v55
	v_lshlrev_b32_e32 v92, 16, v56
	v_and_b32_e32 v93, 0xffff0000, v56
	v_lshlrev_b32_e32 v102, 16, v57
	v_and_b32_e32 v103, 0xffff0000, v57
	v_lshlrev_b32_e32 v104, 16, v58
	v_and_b32_e32 v105, 0xffff0000, v58
	v_lshlrev_b32_e32 v106, 16, v59
	v_and_b32_e32 v107, 0xffff0000, v59
	v_lshlrev_b32_e32 v110, 16, v60
	v_and_b32_e32 v111, 0xffff0000, v60
	v_lshlrev_b32_e32 v112, 16, v61
	v_and_b32_e32 v113, 0xffff0000, v61
	v_lshlrev_b32_e32 v114, 16, v62
	v_and_b32_e32 v115, 0xffff0000, v62
	v_lshlrev_b32_e32 v116, 16, v63
	v_and_b32_e32 v117, 0xffff0000, v63
	v_lshlrev_b32_e32 v108, 16, v64
	v_and_b32_e32 v109, 0xffff0000, v64
	v_lshlrev_b32_e32 v122, 16, v65
	v_and_b32_e32 v123, 0xffff0000, v65
	v_lshlrev_b32_e32 v120, 16, v66
	v_and_b32_e32 v121, 0xffff0000, v66
	v_lshlrev_b32_e32 v118, 16, v67
	v_and_b32_e32 v119, 0xffff0000, v67
	s_branch .LBB0_285

.LBB0_289:
	s_or_b64 exec, exec, s[16:17]
	s_waitcnt lgkmcnt(0)
	v_fmac_f32_e32 v95, v92, v108
	s_waitcnt vmcnt(7)
	v_lshlrev_b32_e32 v92, 16, v3
	v_mul_f32_e32 v92, v95, v92
	v_cvt_pk_bf16_f32 v92, v92, v0
	global_store_short v[152:153], v92, off
	v_fmac_f32_e32 v93, v98, v108
	s_waitcnt vmcnt(7)
	v_lshlrev_b32_e32 v92, 16, v87
	v_mul_f32_e32 v92, v93, v92
	v_cvt_pk_bf16_f32 v92, v92, v0
	global_store_short v[152:153], v92, off offset:2048
	v_fmac_f32_e32 v94, v101, v108
	s_waitcnt vmcnt(7)
	v_lshlrev_b32_e32 v95, 16, v126
	v_mul_f32_e32 v94, v94, v95
	v_cvt_pk_bf16_f32 v94, v94, v0
	global_store_short v[154:155], v94, off
	v_fmac_f32_e32 v96, v103, v108
	s_waitcnt vmcnt(7)
	v_lshlrev_b32_e32 v94, 16, v127
	v_mul_f32_e32 v94, v96, v94
	v_cvt_pk_bf16_f32 v94, v94, v0
	global_store_short v[154:155], v94, off offset:2048
	v_fmac_f32_e32 v97, v104, v108
	s_waitcnt vmcnt(7)
	v_lshlrev_b32_e32 v94, 16, v128
	v_mul_f32_e32 v94, v97, v94
	v_cvt_pk_bf16_f32 v94, v94, v0
	global_store_short v[156:157], v94, off
	v_fmac_f32_e32 v99, v105, v108
	s_waitcnt vmcnt(7)
	v_lshlrev_b32_e32 v94, 16, v129
	v_mul_f32_e32 v94, v99, v94
	v_cvt_pk_bf16_f32 v94, v94, v0
	global_store_short v[156:157], v94, off offset:2048
	v_fmac_f32_e32 v102, v107, v108
	s_waitcnt vmcnt(7)
	v_lshlrev_b32_e32 v94, 16, v130
	v_mul_f32_e32 v94, v102, v94
	v_cvt_pk_bf16_f32 v94, v94, v0
	global_store_short v[158:159], v94, off
	v_fmac_f32_e32 v100, v106, v108
	s_waitcnt vmcnt(7)
	v_lshlrev_b32_e32 v94, 16, v131
	s_add_i32 s52, s52, 1
	v_mul_f32_e32 v94, v100, v94
	v_cvt_pk_bf16_f32 v94, v94, v0
	global_store_short v[158:159], v94, off offset:2048
	v_lshl_add_u64 v[152:153], v[152:153], 0, s[82:83]
	v_lshl_add_u64 v[154:155], v[154:155], 0, s[82:83]
	v_lshl_add_u64 v[156:157], v[156:157], 0, s[82:83]
	v_lshl_add_u64 v[158:159], v[158:159], 0, s[82:83]
	s_cmp_gt_u32 s52, 31
	s_cbranch_scc1 .Lrnn_nog
	global_load_ushort v3, v[152:153], off
	global_load_ushort v87, v[152:153], off offset:2048
	global_load_ushort v126, v[154:155], off
	global_load_ushort v127, v[154:155], off offset:2048
	global_load_ushort v128, v[156:157], off
	global_load_ushort v129, v[156:157], off offset:2048
	global_load_ushort v130, v[158:159], off
	global_load_ushort v131, v[158:159], off offset:2048
.Lrnn_nog:
	s_and_saveexec_b64 s[16:17], s[10:11]
	s_cbranch_execnz .LBB0_291
	s_or_b64 exec, exec, s[16:17]
	s_and_b64 vcc, exec, s[12:13]
	s_cbranch_vccz .LBB0_274
	s_branch .LBB0_292
.LBB0_291:
	s_lshl_b32 s34, s52, 8
	s_and_b32 s34, s34, 0x100
	v_add_u32_e32 v92, s34, v132
	ds_write_b32 v92, v100 offset:62464
	s_or_b64 exec, exec, s[16:17]
	s_and_b64 vcc, exec, s[12:13]
	s_cbranch_vccz .LBB0_274
.LBB0_292:
	s_branch .LBB0_274
.LBB0_293:
	v_cmp_gt_i32_e32 vcc, 64, v84
	s_waitcnt lgkmcnt(0)
	s_barrier
	s_and_saveexec_b64 s[6:7], vcc
	s_xor_b64 s[6:7], exec, s[6:7]
	s_cbranch_execz .LBB0_121
	s_load_dwordx2 s[8:9], s[0:1], 0xc0
	s_lshl_b32 s10, s30, 12
	ds_read_b32 v1, v125 offset:62464
	v_ashrrev_i32_e32 v85, 31, v84
	s_waitcnt lgkmcnt(0)
	s_add_u32 s8, s8, s10
	s_addc_u32 s9, s9, 0
	s_lshl_b32 s10, s80, 2
	s_add_u32 s8, s8, s10
	s_addc_u32 s9, s9, 0
	v_lshl_add_u64 v[2:3], v[84:85], 2, s[8:9]
	v_add_co_u32_e32 v2, vcc, 0x30c60000, v2
	s_nop 1
	v_addc_co_u32_e32 v3, vcc, 0, v3, vcc
	global_store_dword v[2:3], v1, off
	s_branch .LBB0_121
